# weight transpose loop: per-tile wait relaxed to vmcnt(4) so the previous tile's 4 output stores no longer have to complete before the next tile is staged (in-order vmcnt made every tile wait for its o
# baseline (speedup 1.0000x reference)
.LBB0_566:
	s_andn2_b64 vcc, exec, s[0:1]
	s_cbranch_vccnz .LBB0_9
	v_add_u32_e32 v47, 0x400, v34
	v_ashrrev_i32_e32 v45, 3, v35
	v_and_b32_e32 v60, 56, v33
	s_movk_i32 s0, 0x404
	v_ashrrev_i32_e32 v38, 6, v35
	v_ashrrev_i32_e32 v39, 6, v47
	v_add_u32_e32 v49, 0x600, v34
	v_lshlrev_b32_e32 v35, 2, v45
	v_ashrrev_i32_e32 v47, 3, v47
	v_ashrrev_i32_e32 v36, 3, v34
	v_ashrrev_i32_e32 v40, 6, v49
	v_add_u32_e32 v41, 0x800, v34
	v_add_u32_e32 v42, 0xa00, v34
	v_add_u32_e32 v43, 0xc00, v34
	v_add_u32_e32 v34, 0xe00, v34
	v_mad_u32_u24 v46, v60, s0, v35
	v_lshlrev_b32_e32 v35, 2, v47
	v_ashrrev_i32_e32 v49, 3, v49
	v_lshlrev_b32_e32 v33, 2, v36
	v_ashrrev_i32_e32 v41, 6, v41
	v_ashrrev_i32_e32 v42, 6, v42
	v_ashrrev_i32_e32 v43, 6, v43
	v_ashrrev_i32_e32 v44, 6, v34
	v_mad_u32_u24 v48, v60, s0, v35
	v_lshlrev_b32_e32 v35, 2, v49
	v_mad_u32_u24 v37, v60, s0, v33
	v_mul_lo_u32 v33, v52, s0
	v_mul_lo_u32 v53, v38, s0
	v_mul_lo_u32 v54, v39, s0
	v_mul_lo_u32 v55, v40, s0
	v_mul_lo_u32 v56, v41, s0
	v_mul_lo_u32 v57, v42, s0
	v_mul_lo_u32 v58, v43, s0
	v_mul_lo_u32 v34, v44, s0
	v_mad_u32_u24 v50, v60, s0, v35
	s_sub_i32 s0, s56, s48
	s_sub_i32 s0, s0, s51
	s_sub_i32 s6, s0, s53
	s_add_i32 s0, s55, s56
	s_sub_i32 s0, s0, s48
	v_lshlrev_b32_e32 v59, 2, v32
	s_sub_i32 s9, 0, s48
	s_sub_i32 s0, s0, s51
	s_sub_i32 s12, s55, s48
	s_mov_b32 s7, 0
	s_sub_i32 s10, s9, s51
	s_sub_i32 s11, s0, s53
	s_sub_i32 s13, s12, s51
	v_add_u32_e32 v51, v59, v33
	v_add_u32_e32 v53, v59, v53
	v_add_u32_e32 v54, v59, v54
	v_add_u32_e32 v55, v59, v55
	v_add_u32_e32 v56, v59, v56
	v_add_u32_e32 v57, v59, v57
	v_add_u32_e32 v58, v59, v58
	v_add_u32_e32 v59, v59, v34
	v_lshlrev_b32_e32 v144, 2, v32
	v_lshlrev_b32_e32 v32, 1, v60
	s_mov_b32 s14, s55
	s_mov_b32 s15, s54
	s_waitcnt vmcnt(0)
	s_branch .LBB0_570

.LBB0_594:
	s_add_i32 s15, s15, s55
	s_add_i32 s0, s54, s14
	s_cmp_ge_i32 s0, s8
	s_waitcnt vmcnt(4)
	v_mov_b64_e32 v[188:189], v[0:1]
	v_mov_b64_e32 v[190:191], v[2:3]
	v_mov_b64_e32 v[192:193], v[4:5]
	v_mov_b64_e32 v[194:195], v[6:7]
	v_mov_b64_e32 v[196:197], v[8:9]
	v_mov_b64_e32 v[198:199], v[10:11]
	v_mov_b64_e32 v[200:201], v[12:13]
	v_mov_b64_e32 v[202:203], v[14:15]
	v_mov_b64_e32 v[204:205], v[16:17]
	v_mov_b64_e32 v[206:207], v[18:19]
	v_mov_b64_e32 v[208:209], v[20:21]
	v_mov_b64_e32 v[210:211], v[22:23]
	v_mov_b64_e32 v[212:213], v[24:25]
	v_mov_b64_e32 v[214:215], v[26:27]
	v_mov_b64_e32 v[216:217], v[28:29]
	v_mov_b64_e32 v[218:219], v[30:31]
	s_cbranch_scc1 .Ltr_wr
	s_branch .Ltr_next
